# baseline (speedup 1.0000x reference)
; __device__ __forceinline__ float shfl_idx(float v, int srclane) { return __int_as_float(__builtin_amdgcn_ds_bpermute(srclane << 2, __float_as_int(v))); }
; __device__ __forceinline__ float4 ldg16f(const void* p) { typedef float f32x4_ __attribute__((ext_vector_type(4))); const f32x4_ v = *(const __attribute__((address_space(1))) f32x4_*)(p); return make_float4(v.x, v.y, v.z, v.w); }
; __device__ __forceinline__ void rmsnorm_rows(const float* src, const float* __restrict__ gain, void* dstv, const bool OUTF32, int wv, int lane) {
;   const int nw = gridDim.x * 8;
;   for (int row = blockIdx.x * 8 + wv; row < T_; row += nw) {
;     const float* s = src + (long)row * 2048;
;     float4 v[8];
;     float ss = 0.f;
; #pragma unroll
;     for (int i = 0; i < 8; ++i) {
;       v[i] = ldg16f(s + i * 256 + lane * 4);
;       ss += v[i].x * v[i].x + v[i].y * v[i].y + v[i].z * v[i].z + v[i].w * v[i].w;
;     }
; #pragma unroll
;     for (int o = 32; o >= 1; o >>= 1) ss += shfl_idx(ss, lane ^ o);
;     const float rs = rsqrtf(ss * (1.f / 2048.f) + EPS_);
; #pragma unroll
;     for (int i = 0; i < 8; ++i) {
;       const float4 g = ldg16f(gain + i * 256 + lane * 4);
.LBB0_126:
	s_waitcnt vmcnt(0) lgkmcnt(0)
	v_cmp_ne_u64_e32 vcc, 0, v[0:1]
	s_and_saveexec_b64 s[16:17], vcc
	s_cbranch_execz .LBB0_162
	v_readlane_b32 s8, v253, 12
	v_readlane_b32 s9, v253, 13
	s_andn2_b64 vcc, exec, s[8:9]
	s_cbranch_vccnz .LBB0_162
	v_lshlrev_b32_e32 v38, 2, v214
	v_and_b32_e32 v39, 0xfc, v38
	v_lshlrev_b32_e32 v212, 2, v39
	v_lshl_add_u64 v[2:3], v[2:3], 0, v[212:213]
	global_load_dwordx4 v[6:9], v[2:3], off
	global_load_dwordx4 v[10:13], v[2:3], off offset:1024
	global_load_dwordx4 v[14:17], v[2:3], off offset:2048
	global_load_dwordx4 v[18:21], v[2:3], off offset:3072
	v_add_co_u32_e32 v2, vcc, s66, v2
	v_readlane_b32 s18, v254, 27
	s_nop 0
	v_addc_co_u32_e32 v3, vcc, 0, v3, vcc
	global_load_dwordx4 v[22:25], v[2:3], off
	global_load_dwordx4 v[26:29], v[2:3], off offset:1024
	global_load_dwordx4 v[30:33], v[2:3], off offset:2048
	global_load_dwordx4 v[34:37], v[2:3], off offset:3072
	v_readlane_b32 s8, v254, 10
	s_movk_i32 s7, 0x80
	v_readlane_b32 s19, v254, 28
	v_readlane_b32 s9, v254, 11
	v_lshlrev_b32_e32 v2, 1, v39
	v_mov_b32_e32 v3, v213
	v_bitop3_b32 v74, v38, s7, v239 bitop3:0x6c
	v_bitop3_b32 v75, v38, 64, v239 bitop3:0x6c
	v_bitop3_b32 v76, v38, 32, v239 bitop3:0x6c
	v_bitop3_b32 v77, v38, 16, v239 bitop3:0x6c
	v_bitop3_b32 v78, v38, 8, v239 bitop3:0x6c
	v_bitop3_b32 v79, v38, 4, v239 bitop3:0x6c
	v_and_b32_e32 v38, 63, v214
	v_lshl_add_u64 v[66:67], v[4:5], 0, s[18:19]
	v_lshl_add_u64 v[4:5], v[4:5], 0, s[8:9]
	v_readlane_b32 s8, v254, 25
	s_xor_b64 s[12:13], s[12:13], -1
	v_lshlrev_b32_e32 v212, 4, v38
	v_lshl_add_u64 v[4:5], v[4:5], 0, v[2:3]
	v_lshl_add_u64 v[68:69], v[0:1], 0, s[18:19]
	s_mov_b32 s7, s8
	v_readlane_b32 s9, v254, 26
	v_lshl_add_u64 v[80:81], v[68:69], 0, v[212:213]
	global_load_dwordx4 v[96:99], v[80:81], off
	global_load_dwordx4 v[100:103], v[80:81], off offset:1024
	global_load_dwordx4 v[104:107], v[80:81], off offset:2048
	global_load_dwordx4 v[108:111], v[80:81], off offset:3072
	v_add_co_u32_e32 v80, vcc, s66, v80
	s_nop 1
	v_addc_co_u32_e32 v81, vcc, 0, v81, vcc
	global_load_dwordx4 v[112:115], v[80:81], off
	global_load_dwordx4 v[116:119], v[80:81], off offset:1024
	global_load_dwordx4 v[120:123], v[80:81], off offset:2048
	global_load_dwordx4 v[124:127], v[80:81], off offset:3072
	s_branch .LBB0_130

; __device__ __forceinline__ unsigned pack2(float a, float b) { const f32v2_ v = {a, b}; const bf16v2_ r = __builtin_convertvector(v, bf16v2_); return __builtin_bit_cast(unsigned, r); }
; __device__ __forceinline__ float shfl_idx(float v, int srclane) { return __int_as_float(__builtin_amdgcn_ds_bpermute(srclane << 2, __float_as_int(v))); }
; __device__ __forceinline__ void stg8(void* p, unsigned a, unsigned b) { const u32x2 v = {a, b}; *(__attribute__((address_space(1))) u32x2*)(p) = v; }
; __device__ __forceinline__ void stg16f(void* p, float a, float b, float c, float d) { typedef float f32x4_ __attribute__((ext_vector_type(4))); const f32x4_ v = {a, b, c, d}; *(__attribute__((address_space(1))) f32x4_*)(p) = v; }
; __device__ __forceinline__ float4 ldg16f(const void* p) { typedef float f32x4_ __attribute__((ext_vector_type(4))); const f32x4_ v = *(const __attribute__((address_space(1))) f32x4_*)(p); return make_float4(v.x, v.y, v.z, v.w); }
; __device__ __forceinline__ void rmsnorm_rows(const float* src, const float* __restrict__ gain, void* dstv, const bool OUTF32, int wv, int lane) {
;     ...
;   for (int row = blockIdx.x * 8 + wv; row < T_; row += nw) {
;     const float* s = src + (long)row * 2048;
;     float4 v[8];
;     float ss = 0.f;
; #pragma unroll
;     for (int i = 0; i < 8; ++i) {
;       v[i] = ldg16f(s + i * 256 + lane * 4);
;       ss += v[i].x * v[i].x + v[i].y * v[i].y + v[i].z * v[i].z + v[i].w * v[i].w;
;     }
; #pragma unroll
;     for (int o = 32; o >= 1; o >>= 1) ss += shfl_idx(ss, lane ^ o);
;     const float rs = rsqrtf(ss * (1.f / 2048.f) + EPS_);
; #pragma unroll
;     for (int i = 0; i < 8; ++i) {
;       const float4 g = ldg16f(gain + i * 256 + lane * 4);
;       const float a = v[i].x * rs * g.x, b = v[i].y * rs * g.y, c = v[i].z * rs * g.z, d = v[i].w * rs * g.w;
;       if (OUTF32) {
;         stg16f((float*)dstv + (long)row * 2048 + i * 256 + lane * 4, a, b, c, d);
;       } else {
;         stg8((u16*)dstv + (long)row * 2048 + i * 256 + lane * 4, pack2(a, b), pack2(c, d));
.LBB0_130:
	s_waitcnt vmcnt(0)
	v_mov_b64_e32 v[62:63], v[96:97]
	v_mov_b64_e32 v[64:65], v[98:99]
	v_mov_b64_e32 v[58:59], v[100:101]
	v_mov_b64_e32 v[60:61], v[102:103]
	v_mov_b64_e32 v[54:55], v[104:105]
	v_mov_b64_e32 v[56:57], v[106:107]
	v_mov_b64_e32 v[50:51], v[108:109]
	v_mov_b64_e32 v[52:53], v[110:111]
	v_mov_b64_e32 v[46:47], v[112:113]
	v_mov_b64_e32 v[48:49], v[114:115]
	v_mov_b64_e32 v[42:43], v[116:117]
	v_mov_b64_e32 v[44:45], v[118:119]
	v_mov_b64_e32 v[38:39], v[120:121]
	v_mov_b64_e32 v[40:41], v[122:123]
	v_mov_b64_e32 v[0:1], v[124:125]
	v_mov_b64_e32 v[2:3], v[126:127]
	s_add_i32 s18, s7, s6
	s_cmpk_lt_i32 s18, 0x4000
	s_cbranch_scc0 .Lrn_nopf
	v_lshl_add_u64 v[80:81], v[68:69], 0, s[38:39]
	v_lshl_add_u64 v[80:81], v[80:81], 0, v[212:213]
	global_load_dwordx4 v[96:99], v[80:81], off
	global_load_dwordx4 v[100:103], v[80:81], off offset:1024
	global_load_dwordx4 v[104:107], v[80:81], off offset:2048
	global_load_dwordx4 v[108:111], v[80:81], off offset:3072
	v_add_co_u32_e32 v80, vcc, s66, v80
	s_nop 1
	v_addc_co_u32_e32 v81, vcc, 0, v81, vcc
	global_load_dwordx4 v[112:115], v[80:81], off
	global_load_dwordx4 v[116:119], v[80:81], off offset:1024
	global_load_dwordx4 v[120:123], v[80:81], off offset:2048
	global_load_dwordx4 v[124:127], v[80:81], off offset:3072
.Lrn_nopf:
	s_and_b64 s[8:9], exec, s[12:13]
	s_mov_b64 s[18:19], -1
	v_mul_f32_e32 v92, v63, v63
	v_mul_f32_e32 v93, v59, v59
	v_mul_f32_e32 v94, v55, v55
	v_fmac_f32_e32 v92, v62, v62
	v_fmac_f32_e32 v93, v58, v58
	v_mul_f32_e32 v95, v51, v51
	v_fmac_f32_e32 v94, v54, v54
	v_mov_b32_e32 v72, v47
	v_mov_b32_e32 v73, v43
	v_mov_b32_e32 v86, v39
	v_mov_b32_e32 v87, v1
	v_fmac_f32_e32 v92, v64, v64
	v_fmac_f32_e32 v93, v60, v60
	v_fmac_f32_e32 v95, v50, v50
	v_mov_b32_e32 v70, v46
	v_mov_b32_e32 v71, v42
	v_mov_b32_e32 v84, v38
	v_mov_b32_e32 v85, v0
	v_fmac_f32_e32 v94, v56, v56
	v_pk_mul_f32 v[72:73], v[72:73], v[72:73]
	v_pk_mul_f32 v[86:87], v[86:87], v[86:87]
	v_fmac_f32_e32 v92, v65, v65
	v_fmac_f32_e32 v93, v61, v61
	v_mov_b32_e32 v80, v48
	v_mov_b32_e32 v81, v44
	v_fmac_f32_e32 v95, v52, v52
	v_fmac_f32_e32 v94, v57, v57
	v_pk_fma_f32 v[70:71], v[70:71], v[70:71], v[72:73]
	v_pk_fma_f32 v[72:73], v[84:85], v[84:85], v[86:87]
	v_add_f32_e32 v84, v92, v93
	v_mov_b32_e32 v82, v49
	v_mov_b32_e32 v83, v45
	v_fmac_f32_e32 v95, v53, v53
	v_pk_fma_f32 v[70:71], v[80:81], v[80:81], v[70:71]
	v_add_f32_e32 v80, v84, v94
	v_mov_b32_e32 v88, v40
	v_mov_b32_e32 v89, v2
	v_pk_fma_f32 v[70:71], v[82:83], v[82:83], v[70:71]
	v_add_f32_e32 v80, v80, v95
	v_mov_b32_e32 v90, v41
	v_mov_b32_e32 v91, v3
	v_pk_fma_f32 v[72:73], v[88:89], v[88:89], v[72:73]
	v_add_f32_e32 v70, v80, v70
	v_pk_fma_f32 v[72:73], v[90:91], v[90:91], v[72:73]
	v_add_f32_e32 v70, v70, v71
	v_add_f32_e32 v70, v70, v72
	v_add_f32_e32 v70, v70, v73
	ds_bpermute_b32 v71, v74, v70
	s_waitcnt lgkmcnt(0)
	v_add_f32_e32 v70, v70, v71
	ds_bpermute_b32 v71, v75, v70
	s_waitcnt lgkmcnt(0)
	v_add_f32_e32 v70, v70, v71
	ds_bpermute_b32 v71, v76, v70
	s_waitcnt lgkmcnt(0)
	v_add_f32_e32 v70, v70, v71
	ds_bpermute_b32 v71, v77, v70
	s_waitcnt lgkmcnt(0)
	v_add_f32_e32 v70, v70, v71
	ds_bpermute_b32 v71, v78, v70
	s_waitcnt lgkmcnt(0)
	v_add_f32_e32 v70, v70, v71
	ds_bpermute_b32 v71, v79, v70
	s_waitcnt lgkmcnt(0)
	v_add_f32_e32 v70, v70, v71
	v_fmamk_f32 v70, v70, 0x3a000000, v231
	v_mul_f32_e32 v71, 0x4b800000, v70
	v_cmp_gt_f32_e32 vcc, s70, v70
	s_nop 1
	v_cndmask_b32_e32 v70, v70, v71, vcc
	v_rsq_f32_e32 v70, v70
	s_nop 0
	v_mul_f32_e32 v71, 0x45800000, v70
	v_cndmask_b32_e32 v72, v70, v71, vcc
	v_pk_mul_f32 v[62:63], v[62:63], v[72:73] op_sel_hi:[1,0]
	v_pk_mul_f32 v[64:65], v[64:65], v[72:73] op_sel_hi:[1,0]
	v_pk_mul_f32 v[62:63], v[6:7], v[62:63]
	v_pk_mul_f32 v[64:65], v[8:9], v[64:65]
	s_mov_b64 vcc, s[8:9]
	s_cbranch_vccz .LBB0_132
	v_cvt_pk_bf16_f32 v70, v62, v63
	v_cvt_pk_bf16_f32 v71, v64, v65
	global_store_dwordx2 v[4:5], v[70:71], off offset:-3584
	s_mov_b64 s[18:19], 0
